# MLA softmax row-sum accumulation with v_pk_add_f32 (16 instead of 32 adds per tile) on top of v49
# baseline (speedup 1.0000x reference)
; template <bool MLA> __device__ __forceinline__ void attn_unit(const AttnP& P, int b, int hh, int qb, LAS char* lds) {
;     ...
;     const int qlo = q0 + wid * 32, qm = qlo + r32 - 4 * hi;
;     bf16x8 qr[NQF];
;     const size_t qrow = rowbase + qlo + r32;
;     if constexpr (MLA) {
; #pragma unroll
;         for (int d0 = 0; d0 < 8; ++d0) qr[d0] = *(const bf16x8*)(P.QN + qrow * 2048 + hh * 128 + d0 * 16 + hi * 8);
; #pragma unroll
;         for (int d0 = 0; d0 < 4; ++d0) qr[8 + d0] = *(const bf16x8*)(P.QR + qrow * 1024 + hh * 64 + d0 * 16 + hi * 8);
;     } else {
; #pragma unroll
;         for (int d0 = 0; d0 < 4; ++d0) qr[d0] = *(const bf16x8*)(P.QS + qrow * 2048 + hh * 64 + d0 * 16 + hi * 8);
;         if (tid < 128) bias_l[tid] = P.rel[(int)T5B[tid] * 32 + hh] * (1.0f / SCALE);
;     }
;     bf16x8 sk0, sv0;
;     const int sr8 = tid >> 3, ch8 = tid & 7;
;     const bf16_t* Kg; const bf16_t* Vg; const bf16_t* Rg = nullptr;
;     unsigned okA = 0, okB = 0, orp = 0, ovA = 0, ovB = 0;
;     if constexpr (MLA) {
;         Kg = P.KN + rowbase * 2048 + hh * 128; Vg = P.V + rowbase * 2048 + hh * 128; Rg = P.KR + rowbase * 64;
;         { const int rA = 4 * wid + (lane >> 4), rB = rA + 32, cp = lane & 15; okA = (unsigned)(rA * 2048 + ((cp ^ (rA & 7)) << 3)); okB = (unsigned)(rB * 2048 + ((cp ^ (rB & 7)) << 3)); }
;         { const int rr = 8 * wid + (lane >> 3), cp = lane & 7; orp = (unsigned)(rr * 64 + ((cp ^ (rr & 7)) << 3)); }
;         { const int stA = 2 * wid + (lane >> 5), stB = stA + 16; const int kl = (lane & 31) >> 2, c8 = 8 * (lane & 3);
;           const int kkA = (stA >> 2) * 8 + kl, kkB = (stB >> 2) * 8 + kl;
;           const int kA = (kkA & ~0xC) | ((kkA & 4) << 1) | ((kkA & 8) >> 1), kB = (kkB & ~0xC) | ((kkB & 4) << 1) | ((kkB & 8) >> 1);
;           ovA = (unsigned)(kA * 2048 + 32 * (stA & 3) + c8); ovB = (unsigned)(kB * 2048 + 32 * (stB & 3) + c8); }
;     } else { Kg = P.KS + (rowbase + sr8) * 256 + (hh >> 3) * 64 + ch8 * 8; Vg = P.VS + (rowbase + sr8) * 256 + (hh >> 3) * 64 + ch8 * 8; }
;     const int kws = KSWZ64(sr8, ch8), vst0 = v_st<NCB>(sr8, ch8 * 8);
;     ...
;     float m_reg = MLA ? 0.f : P.sinks[hh] * (1.0f / SCALE), l_reg = MLA ? 0.f : 1.f;
;     f32x16 o[NCB];
; #pragma unroll
;     for (int d = 0; d < NCB; ++d) o[d] = f32x16{};
;     const int vb0 = (int)(uintptr_t)V_lds + v_rd_base(lane);
.Lm16_qb_ok:
	s_lshr_b32 s36, s28, 5
	s_and_b32 s63, s36, 15
	s_lshr_b32 s64, s36, 4
	s_lshl_b32 s40, s33, 2
	s_add_u32 s40, s40, 4
	s_lshl_b32 s43, s33, 8
	s_lshl_b32 s36, s4, 5
	s_add_u32 s43, s43, s36
	s_lshl_b32 s36, s64, 14
	s_add_u32 s36, s36, s43
	s_lshl_b32 s37, s36, 12
	s_lshl_b32 s59, s63, 8
	s_add_u32 s37, s37, s59
	s_add_u32 s66, s6, s37
	s_addc_u32 s67, s7, 0
	s_lshl_b32 s37, s36, 11
	s_lshl_b32 s59, s63, 7
	s_add_u32 s37, s37, s59
	s_add_u32 s68, s8, s37
	s_addc_u32 s69, s9, 0
	s_lshl_b32 s37, s64, 26
	s_lshl_b32 s59, s63, 8
	s_add_u32 s37, s37, s59
	s_add_u32 s46, s12, s37
	s_addc_u32 s47, s13, 0
	s_add_u32 s48, s16, s37
	s_addc_u32 s49, s17, 0
	s_lshl_b32 s37, s64, 21
	s_add_u32 s50, s14, s37
	s_addc_u32 s51, s15, 0
	global_load_dwordx4 v[66:69], v237, s[66:67] offset:0
	global_load_dwordx4 v[70:73], v237, s[66:67] offset:64
	global_load_dwordx4 v[74:77], v237, s[66:67] offset:128
	global_load_dwordx4 v[78:81], v237, s[66:67] offset:192
	global_load_dwordx4 v[82:85], v239, s[68:69] offset:0
	global_load_dwordx4 v[86:89], v239, s[68:69] offset:64
	global_load_dwordx4 v[90:93], v238, s[66:67] offset:0
	global_load_dwordx4 v[94:97], v238, s[66:67] offset:64
	global_load_dwordx4 v[98:101], v238, s[66:67] offset:128
	global_load_dwordx4 v[102:105], v238, s[66:67] offset:192
	global_load_dwordx4 v[106:109], v240, s[68:69] offset:0
	global_load_dwordx4 v[110:113], v240, s[68:69] offset:64
	s_mov_b32 s70, 0x8000
	s_mov_b32 s71, 0
	s_add_i32 s36, s5, s70
	s_mov_b32 m0, s36
	s_nop 0
	global_load_lds_dwordx4 v232, s[46:47]
	s_add_i32 m0, s36, 0x2000
	s_nop 0
	global_load_lds_dwordx4 v233, s[46:47]
	s_add_i32 m0, s36, 0x4000
	s_nop 0
	global_load_lds_dwordx4 v234, s[50:51]
	s_add_i32 s36, s5, s71
	s_mov_b32 m0, s36
	s_nop 0
	global_load_lds_dwordx4 v235, s[48:49]
	s_add_i32 m0, s36, 0x2000
	s_nop 0
	global_load_lds_dwordx4 v236, s[48:49]
	s_add_u32 s46, s46, 0x40000
	s_addc_u32 s47, s47, 0
	s_add_u32 s48, s48, 0x40000
	s_addc_u32 s49, s49, 0
	s_add_u32 s50, s50, 0x2000
	s_addc_u32 s51, s51, 0
	v_mov_b32_e32 v2, 0
	v_mov_b32_e32 v3, 0
	v_mov_b32_e32 v4, 0
	v_mov_b32_e32 v5, 0
	v_mov_b32_e32 v6, 0
	v_mov_b32_e32 v7, 0
	v_mov_b32_e32 v8, 0
	v_mov_b32_e32 v9, 0
	v_mov_b32_e32 v10, 0
	v_mov_b32_e32 v11, 0
	v_mov_b32_e32 v12, 0
	v_mov_b32_e32 v13, 0
	v_mov_b32_e32 v14, 0
	v_mov_b32_e32 v15, 0
	v_mov_b32_e32 v16, 0
	v_mov_b32_e32 v17, 0
	v_mov_b32_e32 v18, 0
	v_mov_b32_e32 v19, 0
	v_mov_b32_e32 v20, 0
	v_mov_b32_e32 v21, 0
	v_mov_b32_e32 v22, 0
	v_mov_b32_e32 v23, 0
	v_mov_b32_e32 v24, 0
	v_mov_b32_e32 v25, 0
	v_mov_b32_e32 v26, 0
	v_mov_b32_e32 v27, 0
	v_mov_b32_e32 v28, 0
	v_mov_b32_e32 v29, 0
	v_mov_b32_e32 v30, 0
	v_mov_b32_e32 v31, 0
	v_mov_b32_e32 v32, 0
	v_mov_b32_e32 v33, 0
	v_mov_b32_e32 v34, 0
	v_mov_b32_e32 v35, 0
	v_mov_b32_e32 v36, 0
	v_mov_b32_e32 v37, 0
	v_mov_b32_e32 v38, 0
	v_mov_b32_e32 v39, 0
	v_mov_b32_e32 v40, 0
	v_mov_b32_e32 v41, 0
	v_mov_b32_e32 v42, 0
	v_mov_b32_e32 v43, 0
	v_mov_b32_e32 v44, 0
	v_mov_b32_e32 v45, 0
	v_mov_b32_e32 v46, 0
	v_mov_b32_e32 v47, 0
	v_mov_b32_e32 v48, 0
	v_mov_b32_e32 v49, 0
	v_mov_b32_e32 v50, 0
	v_mov_b32_e32 v51, 0
	v_mov_b32_e32 v52, 0
	v_mov_b32_e32 v53, 0
	v_mov_b32_e32 v54, 0
	v_mov_b32_e32 v55, 0
	v_mov_b32_e32 v56, 0
	v_mov_b32_e32 v57, 0
	v_mov_b32_e32 v58, 0
	v_mov_b32_e32 v59, 0
	v_mov_b32_e32 v60, 0
	v_mov_b32_e32 v61, 0
	v_mov_b32_e32 v62, 0
	v_mov_b32_e32 v63, 0
	v_mov_b32_e32 v64, 0
	v_mov_b32_e32 v65, 0
	v_mov_b32_e32 v216, 0
	v_mov_b32_e32 v217, 0
	v_mov_b32_e32 v218, 0
	v_mov_b32_e32 v208, 0
	v_mov_b32_e32 v209, 0
	v_mov_b32_e32 v210, 0
	v_mov_b32_e32 v211, 0
	v_mov_b32_e32 v250, 0
	v_mov_b32_e32 v251, 0
	v_mov_b32_e32 v219, 0
	v_mov_b32_e32 v212, 0
	v_mov_b32_e32 v213, 0
	v_mov_b32_e32 v214, 0
	v_mov_b32_e32 v215, 0
	s_mov_b32 s41, 0
	s_mov_b32 s42, 0
	s_waitcnt vmcnt(0)
	s_barrier

; #define WLK(n) do { asm volatile("s_waitcnt lgkmcnt(" #n ")" ::: "memory"); SBAR(); } while (0)
; #define RDN(S, dd, off) do { const int a_ = rb + (((dd) * 32 + h16) ^ sw); KRD(S##0, a_, off); KRD(S##1, a_, 8192 + (off)); } while (0)
; #define RDR(S, ks) do { const int a_ = rr + (((((ks) * 2 + hi)) ^ (r32 & 7)) << 4); KRD(S##0, a_, 0); KRD(S##1, a_, 4096); } while (0)
; #define MM1(S, d) do { p0 = __builtin_amdgcn_mfma_f32_32x32x16_bf16(S##0, qr[d], p0, 0, 0, 0); p1 = __builtin_amdgcn_mfma_f32_32x32x16_bf16(S##1, qr[d], p1, 0, 0, 0); } while (0)
; __device__ __forceinline__ void qk_mla(f32x16& p0, f32x16& p1, int kaddr, int r32, int hi, const bf16x8* qr) {
;     const int rb = kaddr + r32 * 256, sw = (r32 & 7) << 4, h16 = hi * 16;
;     const int rr = kaddr + 16384 + r32 * 128;
;     ...
;     bf16x8 A0, A1, B0, B1;
;     RDN(A, 0, 0); RDN(B, 1, 0);
;     WLK(2); MM1(A, 0); RDN(A, 2, 0);
;     WLK(2); MM1(B, 1); RDN(B, 3, 0);
;     WLK(2); MM1(A, 2); RDN(A, 0, 128);
;     WLK(2); MM1(B, 3); RDN(B, 1, 128);
;     WLK(2); MM1(A, 4); RDN(A, 2, 128);
;     WLK(2); MM1(B, 5); RDN(B, 3, 128);
;     WLK(2); MM1(A, 6); RDR(A, 0);
;     WLK(2); MM1(B, 7); RDR(B, 1);
;     WLK(2); MM1(A, 8); RDR(A, 2);
;     WLK(2); MM1(B, 9); RDR(B, 3);
;     WLK(2); MM1(A, 10);
;     WLK(0); MM1(B, 11);
; template <bool MLA> __device__ __forceinline__ void attn_unit(const AttnP& P, int b, int hh, int qb, LAS char* lds) {
;     ...
;         const int kb = kbase0 + 64 * t;
;         const bool act = (kb <= qlo + 31) && (MLA || kb + 63 >= qlo - (W - 1));
;         if (act) {
;             f32x16 p0 = f32x16{}, p1 = f32x16{};
;             if constexpr (MLA) {
; #pragma unroll
;                 for (int r = 0; r < 16; ++r) { p0[r] = -m_reg; p1[r] = -m_reg; } }
;             if constexpr (MLA) { qk_mla(p0, p1, (int)(uintptr_t)K_lds + buf * KBYTES, r32, hi, qr); }
;             else { qk64(p0, p1, K_lds + buf * KBYTES, r32, hi, qr); }
;             const int dq = qm - kb;
;             if constexpr (!MLA) {
; #pragma unroll
;                 for (int r = 0; r < 16; ++r) { const int c = (r & 3) + 8 * (r >> 2); p0[r] += bias_l[(dq - c) & 127]; p1[r] += bias_l[(dq - c - 32) & 127]; }
;             }
;             if (kb + 63 > qlo || (!MLA && kb <= qlo + 31 - W)) mask_tile(p0, p1, dq, (unsigned)W);
.Lm16_noload:
	s_add_u32 s36, s43, 31
	s_cmp_gt_u32 s42, s36
	s_cbranch_scc1 .Lm16_tile_end
	v_add_u32_e32 v228, s70, v224
	v_add_u32_e32 v229, s70, v225
	v_add_u32_e32 v230, s71, v226
	v_add_u32_e32 v231, s71, v227
	ds_read_b128 v[180:183], v228 offset:0
	ds_read_b128 v[184:187], v228 offset:2048
	ds_read_b128 v[188:191], v228 offset:4096
	ds_read_b128 v[192:195], v228 offset:6144
	s_waitcnt lgkmcnt(3)
	v_mfma_f32_16x16x32_bf16 v[114:117], v[180:183], v[66:69], v[208:211]
	v_mfma_f32_16x16x32_bf16 v[118:121], v[180:183], v[90:93], v[212:215]
	ds_read_b128 v[180:183], v229 offset:0
	s_waitcnt lgkmcnt(3)
	v_mfma_f32_16x16x32_bf16 v[122:125], v[184:187], v[66:69], v[208:211]
	v_mfma_f32_16x16x32_bf16 v[126:129], v[184:187], v[90:93], v[212:215]
	ds_read_b128 v[184:187], v229 offset:2048
	s_waitcnt lgkmcnt(3)
	v_mfma_f32_16x16x32_bf16 v[130:133], v[188:191], v[66:69], v[208:211]
	v_mfma_f32_16x16x32_bf16 v[134:137], v[188:191], v[90:93], v[212:215]
	ds_read_b128 v[188:191], v229 offset:4096
	s_waitcnt lgkmcnt(3)
	v_mfma_f32_16x16x32_bf16 v[138:141], v[192:195], v[66:69], v[208:211]
	v_mfma_f32_16x16x32_bf16 v[142:145], v[192:195], v[90:93], v[212:215]
	ds_read_b128 v[192:195], v229 offset:6144
	s_waitcnt lgkmcnt(3)
	v_mfma_f32_16x16x32_bf16 v[114:117], v[180:183], v[70:73], v[114:117]
	v_mfma_f32_16x16x32_bf16 v[118:121], v[180:183], v[94:97], v[118:121]
	ds_read_b128 v[180:183], v228 offset:8192
	s_waitcnt lgkmcnt(3)
	v_mfma_f32_16x16x32_bf16 v[122:125], v[184:187], v[70:73], v[122:125]
	v_mfma_f32_16x16x32_bf16 v[126:129], v[184:187], v[94:97], v[126:129]
	ds_read_b128 v[184:187], v228 offset:10240
	s_waitcnt lgkmcnt(3)
	v_mfma_f32_16x16x32_bf16 v[130:133], v[188:191], v[70:73], v[130:133]
	v_mfma_f32_16x16x32_bf16 v[134:137], v[188:191], v[94:97], v[134:137]
	ds_read_b128 v[188:191], v228 offset:12288
	s_waitcnt lgkmcnt(3)
	v_mfma_f32_16x16x32_bf16 v[138:141], v[192:195], v[70:73], v[138:141]
	v_mfma_f32_16x16x32_bf16 v[142:145], v[192:195], v[94:97], v[142:145]
	ds_read_b128 v[192:195], v228 offset:14336
	s_waitcnt lgkmcnt(3)
	v_mfma_f32_16x16x32_bf16 v[114:117], v[180:183], v[74:77], v[114:117]
	v_mfma_f32_16x16x32_bf16 v[118:121], v[180:183], v[98:101], v[118:121]
	ds_read_b128 v[180:183], v229 offset:8192
	s_waitcnt lgkmcnt(3)
	v_mfma_f32_16x16x32_bf16 v[122:125], v[184:187], v[74:77], v[122:125]
	v_mfma_f32_16x16x32_bf16 v[126:129], v[184:187], v[98:101], v[126:129]
	ds_read_b128 v[184:187], v229 offset:10240
	s_waitcnt lgkmcnt(3)
	v_mfma_f32_16x16x32_bf16 v[130:133], v[188:191], v[74:77], v[130:133]
	v_mfma_f32_16x16x32_bf16 v[134:137], v[188:191], v[98:101], v[134:137]
	ds_read_b128 v[188:191], v229 offset:12288
	s_waitcnt lgkmcnt(3)
	v_mfma_f32_16x16x32_bf16 v[138:141], v[192:195], v[74:77], v[138:141]
	v_mfma_f32_16x16x32_bf16 v[142:145], v[192:195], v[98:101], v[142:145]
	ds_read_b128 v[192:195], v229 offset:14336
	s_waitcnt lgkmcnt(3)
	v_mfma_f32_16x16x32_bf16 v[114:117], v[180:183], v[78:81], v[114:117]
	v_mfma_f32_16x16x32_bf16 v[118:121], v[180:183], v[102:105], v[118:121]
	ds_read_b128 v[180:183], v228 offset:16384
	s_waitcnt lgkmcnt(3)
	v_mfma_f32_16x16x32_bf16 v[122:125], v[184:187], v[78:81], v[122:125]
	v_mfma_f32_16x16x32_bf16 v[126:129], v[184:187], v[102:105], v[126:129]
	ds_read_b128 v[184:187], v228 offset:18432
	s_waitcnt lgkmcnt(3)
	v_mfma_f32_16x16x32_bf16 v[130:133], v[188:191], v[78:81], v[130:133]
	v_mfma_f32_16x16x32_bf16 v[134:137], v[188:191], v[102:105], v[134:137]
	ds_read_b128 v[188:191], v228 offset:20480
	s_waitcnt lgkmcnt(3)
	v_mfma_f32_16x16x32_bf16 v[138:141], v[192:195], v[78:81], v[138:141]
	v_mfma_f32_16x16x32_bf16 v[142:145], v[192:195], v[102:105], v[142:145]
	ds_read_b128 v[192:195], v228 offset:22528
	s_waitcnt lgkmcnt(3)
	v_mfma_f32_16x16x32_bf16 v[114:117], v[180:183], v[82:85], v[114:117]
	v_mfma_f32_16x16x32_bf16 v[118:121], v[180:183], v[106:109], v[118:121]
	ds_read_b128 v[180:183], v229 offset:16384
	s_waitcnt lgkmcnt(3)
	v_mfma_f32_16x16x32_bf16 v[122:125], v[184:187], v[82:85], v[122:125]
	v_mfma_f32_16x16x32_bf16 v[126:129], v[184:187], v[106:109], v[126:129]
	ds_read_b128 v[184:187], v229 offset:18432
	s_waitcnt lgkmcnt(3)
	v_mfma_f32_16x16x32_bf16 v[130:133], v[188:191], v[82:85], v[130:133]
	v_mfma_f32_16x16x32_bf16 v[134:137], v[188:191], v[106:109], v[134:137]
	ds_read_b128 v[188:191], v229 offset:20480
	s_waitcnt lgkmcnt(3)
	v_mfma_f32_16x16x32_bf16 v[138:141], v[192:195], v[82:85], v[138:141]
	v_mfma_f32_16x16x32_bf16 v[142:145], v[192:195], v[106:109], v[142:145]
	ds_read_b128 v[192:195], v229 offset:22528
	s_waitcnt lgkmcnt(3)
	v_mfma_f32_16x16x32_bf16 v[114:117], v[180:183], v[86:89], v[114:117]
	v_mfma_f32_16x16x32_bf16 v[118:121], v[180:183], v[110:113], v[118:121]
	s_waitcnt lgkmcnt(2)
	v_mfma_f32_16x16x32_bf16 v[122:125], v[184:187], v[86:89], v[122:125]
	v_mfma_f32_16x16x32_bf16 v[126:129], v[184:187], v[110:113], v[126:129]
	s_waitcnt lgkmcnt(1)
	v_mfma_f32_16x16x32_bf16 v[130:133], v[188:191], v[86:89], v[130:133]
	v_mfma_f32_16x16x32_bf16 v[134:137], v[188:191], v[110:113], v[134:137]
	s_waitcnt lgkmcnt(0)
	v_mfma_f32_16x16x32_bf16 v[138:141], v[192:195], v[86:89], v[138:141]
	v_mfma_f32_16x16x32_bf16 v[142:145], v[192:195], v[110:113], v[142:145]
	s_nop 7
	s_add_u32 s36, s42, 63
	s_cmp_gt_u32 s36, s43
	s_cbranch_scc0 .Lm16_nomask
; __device__ __forceinline__ void mask_tile(f32x16& p0, f32x16& p1, int dq, unsigned W) {
;     const float NEG = -__builtin_inff();
; #pragma unroll
;     for (int r = 0; r < 16; ++r) { const int c = (r & 3) + 8 * (r >> 2);
;         if ((unsigned)(dq - c) >= W) p0[r] = NEG;
;         if ((unsigned)(dq - c - 32) >= W) p1[r] = NEG; }
; }
; template <int SCALE_E6> __device__ __forceinline__ void partialSM(f32x16& p0, f32x16& p1, float& m_reg, float& mn, float& alpha) {
;     constexpr float SCALE = SCALE_E6 * 1e-9f; constexpr float C2 = 1.4426950408889634f * SCALE;
;     float pmax = p0[0];
; #pragma unroll
;     for (int r = 1; r < 16; ++r) pmax = fmaxf(pmax, p0[r]);
; #pragma unroll
;     for (int r = 0; r < 16; ++r) pmax = fmaxf(pmax, p1[r]);
;     { auto rr = __builtin_amdgcn_permlane32_swap(__float_as_uint(pmax), __float_as_uint(pmax), false, false);
;       pmax = fmaxf(__uint_as_float(rr[0]), __uint_as_float(rr[1])); }
;     if (__builtin_expect(__all((pmax - m_reg) * SCALE <= THR), 1)) { mn = m_reg; alpha = 1.f; }
;     else { mn = fmaxf(m_reg, pmax); alpha = __builtin_amdgcn_exp2f((m_reg - mn) * C2); m_reg = mn; }
;     const float mnL = -mn * C2;
; #pragma unroll
;     for (int r = 0; r < 16; ++r) p0[r] = fmaf(p0[r], C2, mnL);
; #pragma unroll
;     for (int r = 0; r < 16; ++r) p1[r] = fmaf(p1[r], C2, mnL);
; #pragma unroll
;     for (int r = 0; r < 16; ++r) p0[r] = __builtin_amdgcn_exp2f(p0[r]);
; }
; __device__ __forceinline__ void partialSM_pre(f32x16& p0, f32x16& p1, float& m_reg, float& alpha) {
;     constexpr float THR2 = THR * 1.4426950408889634f;
;     float pmax = p0[0];
; #pragma unroll
;     for (int r = 1; r < 16; ++r) pmax = fmaxf(pmax, p0[r]);
; #pragma unroll
;     for (int r = 0; r < 16; ++r) pmax = fmaxf(pmax, p1[r]);
;     { auto rr = __builtin_amdgcn_permlane32_swap(__float_as_uint(pmax), __float_as_uint(pmax), false, false);
;       pmax = fmaxf(__uint_as_float(rr[0]), __uint_as_float(rr[1])); }
;     if (__builtin_expect(__all(pmax <= THR2), 1)) { alpha = 1.f; }
;     else { const float d = fmaxf(pmax, 0.f); m_reg += d; alpha = __builtin_amdgcn_exp2f(-d);
; #pragma unroll
;         for (int r = 0; r < 16; ++r) { p0[r] -= d; p1[r] -= d; } }
; #pragma unroll
;     for (int r = 0; r < 16; ++r) p0[r] = __builtin_amdgcn_exp2f(p0[r]);
; }
	s_sub_u32 s36, s43, s42
	v_add_u32_e32 v244, s36, v243
	v_cmp_gt_i32_e32 vcc, 0, v244
	s_nop 1
	v_cndmask_b32_e32 v114, v114, v245, vcc
	v_cmp_gt_i32_e32 vcc, 1, v244
	s_nop 1
	v_cndmask_b32_e32 v115, v115, v245, vcc
	v_cmp_gt_i32_e32 vcc, 2, v244
	s_nop 1
	v_cndmask_b32_e32 v116, v116, v245, vcc
	v_cmp_gt_i32_e32 vcc, 3, v244
	s_nop 1
	v_cndmask_b32_e32 v117, v117, v245, vcc
	v_cmp_gt_i32_e32 vcc, -16, v244
	s_nop 1
	v_cndmask_b32_e32 v118, v118, v245, vcc
	v_cmp_gt_i32_e32 vcc, -15, v244
	s_nop 1
	v_cndmask_b32_e32 v119, v119, v245, vcc
	v_cmp_gt_i32_e32 vcc, -14, v244
	s_nop 1
	v_cndmask_b32_e32 v120, v120, v245, vcc
	v_cmp_gt_i32_e32 vcc, -13, v244
	s_nop 1
	v_cndmask_b32_e32 v121, v121, v245, vcc
	v_cmp_gt_i32_e32 vcc, 16, v244
	s_nop 1
	v_cndmask_b32_e32 v122, v122, v245, vcc
	v_cmp_gt_i32_e32 vcc, 17, v244
	s_nop 1
	v_cndmask_b32_e32 v123, v123, v245, vcc
	v_cmp_gt_i32_e32 vcc, 18, v244
	s_nop 1
	v_cndmask_b32_e32 v124, v124, v245, vcc
	v_cmp_gt_i32_e32 vcc, 19, v244
	s_nop 1
	v_cndmask_b32_e32 v125, v125, v245, vcc
	v_cmp_gt_i32_e32 vcc, 0, v244
	s_nop 1
	v_cndmask_b32_e32 v126, v126, v245, vcc
	v_cmp_gt_i32_e32 vcc, 1, v244
	s_nop 1
	v_cndmask_b32_e32 v127, v127, v245, vcc
	v_cmp_gt_i32_e32 vcc, 2, v244
	s_nop 1
	v_cndmask_b32_e32 v128, v128, v245, vcc
	v_cmp_gt_i32_e32 vcc, 3, v244
	s_nop 1
	v_cndmask_b32_e32 v129, v129, v245, vcc
	v_cmp_gt_i32_e32 vcc, 32, v244
	s_nop 1
	v_cndmask_b32_e32 v130, v130, v245, vcc
	v_cmp_gt_i32_e32 vcc, 33, v244
	s_nop 1
	v_cndmask_b32_e32 v131, v131, v245, vcc
	v_cmp_gt_i32_e32 vcc, 34, v244
	s_nop 1
	v_cndmask_b32_e32 v132, v132, v245, vcc
	v_cmp_gt_i32_e32 vcc, 35, v244
	s_nop 1
	v_cndmask_b32_e32 v133, v133, v245, vcc
	v_cmp_gt_i32_e32 vcc, 16, v244
	s_nop 1
	v_cndmask_b32_e32 v134, v134, v245, vcc
	v_cmp_gt_i32_e32 vcc, 17, v244
	s_nop 1
	v_cndmask_b32_e32 v135, v135, v245, vcc
	v_cmp_gt_i32_e32 vcc, 18, v244
	s_nop 1
	v_cndmask_b32_e32 v136, v136, v245, vcc
	v_cmp_gt_i32_e32 vcc, 19, v244
	s_nop 1
	v_cndmask_b32_e32 v137, v137, v245, vcc
	v_cmp_gt_i32_e32 vcc, 48, v244
	s_nop 1
	v_cndmask_b32_e32 v138, v138, v245, vcc
	v_cmp_gt_i32_e32 vcc, 49, v244
	s_nop 1
	v_cndmask_b32_e32 v139, v139, v245, vcc
	v_cmp_gt_i32_e32 vcc, 50, v244
	s_nop 1
	v_cndmask_b32_e32 v140, v140, v245, vcc
	v_cmp_gt_i32_e32 vcc, 51, v244
	s_nop 1
	v_cndmask_b32_e32 v141, v141, v245, vcc
	v_cmp_gt_i32_e32 vcc, 32, v244
	s_nop 1
	v_cndmask_b32_e32 v142, v142, v245, vcc
	v_cmp_gt_i32_e32 vcc, 33, v244
	s_nop 1
	v_cndmask_b32_e32 v143, v143, v245, vcc
	v_cmp_gt_i32_e32 vcc, 34, v244
	s_nop 1
	v_cndmask_b32_e32 v144, v144, v245, vcc
	v_cmp_gt_i32_e32 vcc, 35, v244
	s_nop 1
	v_cndmask_b32_e32 v145, v145, v245, vcc
.Lm16_nomask:
	v_max3_f32 v220, v114, v115, v116
	v_max3_f32 v220, v220, v117, v118
	v_max3_f32 v220, v220, v119, v120
	v_max3_f32 v220, v220, v121, v122
	v_max3_f32 v220, v220, v123, v124
	v_max3_f32 v220, v220, v125, v126
	v_max3_f32 v220, v220, v127, v128
	v_max3_f32 v220, v220, v129, v130
	v_max3_f32 v220, v220, v131, v132
	v_max3_f32 v220, v220, v133, v134
	v_max3_f32 v220, v220, v135, v136
	v_max3_f32 v220, v220, v137, v138
	v_max3_f32 v220, v220, v139, v140
	v_max3_f32 v220, v220, v141, v142
	v_max3_f32 v220, v220, v143, v144
	v_max_f32_e32 v220, v220, v145
	v_cmp_ge_f32_e32 vcc, s72, v220
	s_cmp_eq_u64 vcc, exec
	s_cbranch_scc1 .Lm16_exp
	v_max3_f32 v220, v114, v115, v116
	v_max3_f32 v220, v220, v117, v122
	v_max3_f32 v220, v220, v123, v124
	v_max3_f32 v220, v220, v125, v130
	v_max3_f32 v220, v220, v131, v132
	v_max3_f32 v220, v220, v133, v138
	v_max3_f32 v220, v220, v139, v140
	v_max_f32_e32 v220, v220, v141
	ds_bpermute_b32 v221, v246, v220
	s_waitcnt lgkmcnt(0)
	v_max_f32_e32 v220, v220, v221
	ds_bpermute_b32 v221, v247, v220
	s_waitcnt lgkmcnt(0)
	v_max_f32_e32 v220, v220, v221
	v_max_f32_e32 v221, 0, v220
	v_add_f32_e32 v218, v218, v221
	v_exp_f32_e64 v222, -v221
	v_sub_f32_e32 v114, v114, v221
	v_sub_f32_e32 v115, v115, v221
	v_sub_f32_e32 v116, v116, v221
	v_sub_f32_e32 v117, v117, v221
	v_sub_f32_e32 v122, v122, v221
	v_sub_f32_e32 v123, v123, v221
	v_sub_f32_e32 v124, v124, v221
	v_sub_f32_e32 v125, v125, v221
	v_sub_f32_e32 v130, v130, v221
	v_sub_f32_e32 v131, v131, v221
	v_sub_f32_e32 v132, v132, v221
	v_sub_f32_e32 v133, v133, v221
	v_sub_f32_e32 v138, v138, v221
	v_sub_f32_e32 v139, v139, v221
	v_sub_f32_e32 v140, v140, v221
	v_sub_f32_e32 v141, v141, v221
	v_mul_f32_e32 v216, v216, v222
	v_mul_f32_e32 v217, v217, v222
	v_mul_f32_e32 v2, v2, v222
	v_mul_f32_e32 v3, v3, v222
	v_mul_f32_e32 v4, v4, v222
	v_mul_f32_e32 v5, v5, v222
	v_mul_f32_e32 v10, v10, v222
	v_mul_f32_e32 v11, v11, v222
	v_mul_f32_e32 v12, v12, v222
	v_mul_f32_e32 v13, v13, v222
	v_mul_f32_e32 v18, v18, v222
	v_mul_f32_e32 v19, v19, v222
	v_mul_f32_e32 v20, v20, v222
	v_mul_f32_e32 v21, v21, v222
	v_mul_f32_e32 v26, v26, v222
	v_mul_f32_e32 v27, v27, v222
	v_mul_f32_e32 v28, v28, v222
	v_mul_f32_e32 v29, v29, v222
	v_mul_f32_e32 v34, v34, v222
	v_mul_f32_e32 v35, v35, v222
	v_mul_f32_e32 v36, v36, v222
	v_mul_f32_e32 v37, v37, v222
	v_mul_f32_e32 v42, v42, v222
	v_mul_f32_e32 v43, v43, v222
	v_mul_f32_e32 v44, v44, v222
	v_mul_f32_e32 v45, v45, v222
	v_mul_f32_e32 v50, v50, v222
	v_mul_f32_e32 v51, v51, v222
	v_mul_f32_e32 v52, v52, v222
	v_mul_f32_e32 v53, v53, v222
	v_mul_f32_e32 v58, v58, v222
	v_mul_f32_e32 v59, v59, v222
	v_mul_f32_e32 v60, v60, v222
	v_mul_f32_e32 v61, v61, v222
	v_xor_b32_e32 v208, 0x80000000, v218
	v_xor_b32_e32 v209, 0x80000000, v218
	v_xor_b32_e32 v210, 0x80000000, v218
	v_xor_b32_e32 v211, 0x80000000, v218
	v_max3_f32 v220, v118, v119, v120
	v_max3_f32 v220, v220, v121, v126
	v_max3_f32 v220, v220, v127, v128
	v_max3_f32 v220, v220, v129, v134
	v_max3_f32 v220, v220, v135, v136
	v_max3_f32 v220, v220, v137, v142
	v_max3_f32 v220, v220, v143, v144
	v_max_f32_e32 v220, v220, v145
	ds_bpermute_b32 v221, v246, v220
	s_waitcnt lgkmcnt(0)
; #define PV_RD(S, d0) do { constexpr int b_ = (d0) * 512; TRRD(S##l0, b_); TRRD(S##h0, b_ + KS_ / 2); TRRD(S##l1, b_ + KS_); TRRD(S##h1, b_ + KS_ + KS_ / 2); TRRD(S##l2, b_ + 2 * KS_); TRRD(S##h2, b_ + 2 * KS_ + KS_ / 2); TRRD(S##l3, b_ + 3 * KS_); TRRD(S##h3, b_ + 3 * KS_ + KS_ / 2); } while (0)
; #define WL(n) do { asm volatile("s_waitcnt lgkmcnt(" #n ")" ::: "memory"); SBAR(); } while (0)
; __device__ __forceinline__ void partialSM_pre(f32x16& p0, f32x16& p1, float& m_reg, float& alpha) {
;     ...
;     else { const float d = fmaxf(pmax, 0.f); m_reg += d; alpha = __builtin_amdgcn_exp2f(-d);
; #pragma unroll
;         for (int r = 0; r < 16; ++r) { p0[r] -= d; p1[r] -= d; } }
; #pragma unroll
;     for (int r = 0; r < 16; ++r) p0[r] = __builtin_amdgcn_exp2f(p0[r]);
; }
; __device__ __forceinline__ void finishSM(f32x16& p0, f32x16& p1, float alpha, float& l_reg, bf16x8& pa0, bf16x8& pa1, bf16x8& pa2, bf16x8& pa3) {
; #pragma unroll
;     for (int r = 0; r < 16; ++r) p1[r] = __builtin_amdgcn_exp2f(p1[r]);
;     float ps = 0;
; #pragma unroll
;     for (int r = 0; r < 16; ++r) ps += p0[r];
; #pragma unroll
;     for (int r = 0; r < 16; ++r) ps += p1[r];
;     { auto rr = __builtin_amdgcn_permlane32_swap(__float_as_uint(ps), __float_as_uint(ps), false, false);
;       ps = __uint_as_float(rr[0]) + __uint_as_float(rr[1]); }
;     l_reg = l_reg * alpha + ps;
; template <int NCB> __device__ __forceinline__ void pv_tile(f32x16* o, int vb, bf16x8 pa0, bf16x8 pa1, bf16x8 pa2, bf16x8 pa3) {
;     ...
;     constexpr int KS_ = NCB * 1024;
;     ...
;     s16x4 Al0, Al1, Al2, Al3, Ah0, Ah1, Ah2, Ah3, Bl0, Bl1, Bl2, Bl3, Bh0, Bh1, Bh2, Bh3;
;     PV_RD(A, 0); PV_RD(B, 1); WL(8); PV_MM(A, 0);
;     if constexpr (NCB == 4) { PV_RD(A, 2); WL(8); PV_MM(B, 1); PV_RD(B, 3); WL(8); PV_MM(A, 2); WL(0); PV_MM(B, 3); }
	v_max_f32_e32 v220, v220, v221
	ds_bpermute_b32 v221, v247, v220
	s_waitcnt lgkmcnt(0)
	v_max_f32_e32 v220, v220, v221
	v_max_f32_e32 v221, 0, v220
	v_add_f32_e32 v219, v219, v221
	v_exp_f32_e64 v222, -v221
	v_sub_f32_e32 v118, v118, v221
	v_sub_f32_e32 v119, v119, v221
	v_sub_f32_e32 v120, v120, v221
	v_sub_f32_e32 v121, v121, v221
	v_sub_f32_e32 v126, v126, v221
	v_sub_f32_e32 v127, v127, v221
	v_sub_f32_e32 v128, v128, v221
	v_sub_f32_e32 v129, v129, v221
	v_sub_f32_e32 v134, v134, v221
	v_sub_f32_e32 v135, v135, v221
	v_sub_f32_e32 v136, v136, v221
	v_sub_f32_e32 v137, v137, v221
	v_sub_f32_e32 v142, v142, v221
	v_sub_f32_e32 v143, v143, v221
	v_sub_f32_e32 v144, v144, v221
	v_sub_f32_e32 v145, v145, v221
	v_mul_f32_e32 v250, v250, v222
	v_mul_f32_e32 v251, v251, v222
	v_mul_f32_e32 v6, v6, v222
	v_mul_f32_e32 v7, v7, v222
	v_mul_f32_e32 v8, v8, v222
	v_mul_f32_e32 v9, v9, v222
	v_mul_f32_e32 v14, v14, v222
	v_mul_f32_e32 v15, v15, v222
	v_mul_f32_e32 v16, v16, v222
	v_mul_f32_e32 v17, v17, v222
	v_mul_f32_e32 v22, v22, v222
	v_mul_f32_e32 v23, v23, v222
	v_mul_f32_e32 v24, v24, v222
	v_mul_f32_e32 v25, v25, v222
	v_mul_f32_e32 v30, v30, v222
	v_mul_f32_e32 v31, v31, v222
	v_mul_f32_e32 v32, v32, v222
	v_mul_f32_e32 v33, v33, v222
	v_mul_f32_e32 v38, v38, v222
	v_mul_f32_e32 v39, v39, v222
	v_mul_f32_e32 v40, v40, v222
	v_mul_f32_e32 v41, v41, v222
	v_mul_f32_e32 v46, v46, v222
	v_mul_f32_e32 v47, v47, v222
	v_mul_f32_e32 v48, v48, v222
	v_mul_f32_e32 v49, v49, v222
	v_mul_f32_e32 v54, v54, v222
	v_mul_f32_e32 v55, v55, v222
	v_mul_f32_e32 v56, v56, v222
	v_mul_f32_e32 v57, v57, v222
	v_mul_f32_e32 v62, v62, v222
	v_mul_f32_e32 v63, v63, v222
	v_mul_f32_e32 v64, v64, v222
	v_mul_f32_e32 v65, v65, v222
	v_xor_b32_e32 v212, 0x80000000, v219
	v_xor_b32_e32 v213, 0x80000000, v219
	v_xor_b32_e32 v214, 0x80000000, v219
	v_xor_b32_e32 v215, 0x80000000, v219
.Lm16_exp:
	v_exp_f32_e32 v114, v114
	v_exp_f32_e32 v115, v115
	v_exp_f32_e32 v116, v116
	v_exp_f32_e32 v117, v117
	v_exp_f32_e32 v118, v118
	v_exp_f32_e32 v119, v119
	v_exp_f32_e32 v120, v120
	v_exp_f32_e32 v121, v121
	v_exp_f32_e32 v122, v122
	v_exp_f32_e32 v123, v123
	v_exp_f32_e32 v124, v124
	v_exp_f32_e32 v125, v125
	v_exp_f32_e32 v126, v126
	v_exp_f32_e32 v127, v127
	v_exp_f32_e32 v128, v128
	v_exp_f32_e32 v129, v129
	v_exp_f32_e32 v130, v130
	v_exp_f32_e32 v131, v131
	v_exp_f32_e32 v132, v132
	v_exp_f32_e32 v133, v133
	v_exp_f32_e32 v134, v134
	v_exp_f32_e32 v135, v135
	v_exp_f32_e32 v136, v136
	v_exp_f32_e32 v137, v137
	v_exp_f32_e32 v138, v138
	v_exp_f32_e32 v139, v139
	v_exp_f32_e32 v140, v140
	v_exp_f32_e32 v141, v141
	v_exp_f32_e32 v142, v142
	v_exp_f32_e32 v143, v143
	v_exp_f32_e32 v144, v144
	v_exp_f32_e32 v145, v145
	v_pk_add_f32 v[216:217], v[216:217], v[114:115]
	v_pk_add_f32 v[250:251], v[250:251], v[118:119]
	v_pk_add_f32 v[216:217], v[216:217], v[116:117]
	v_pk_add_f32 v[250:251], v[250:251], v[120:121]
	v_pk_add_f32 v[216:217], v[216:217], v[122:123]
	v_pk_add_f32 v[250:251], v[250:251], v[126:127]
	v_pk_add_f32 v[216:217], v[216:217], v[124:125]
	v_pk_add_f32 v[250:251], v[250:251], v[128:129]
	v_pk_add_f32 v[216:217], v[216:217], v[130:131]
	v_pk_add_f32 v[250:251], v[250:251], v[134:135]
	v_pk_add_f32 v[216:217], v[216:217], v[132:133]
	v_pk_add_f32 v[250:251], v[250:251], v[136:137]
	v_pk_add_f32 v[216:217], v[216:217], v[138:139]
	v_pk_add_f32 v[250:251], v[250:251], v[142:143]
	v_pk_add_f32 v[216:217], v[216:217], v[140:141]
	v_pk_add_f32 v[250:251], v[250:251], v[144:145]
	v_cvt_pk_bf16_f32 v164, v114, v115
	v_cvt_pk_bf16_f32 v165, v116, v117
	v_cvt_pk_bf16_f32 v166, v122, v123
	v_cvt_pk_bf16_f32 v167, v124, v125
	v_cvt_pk_bf16_f32 v168, v130, v131
	v_cvt_pk_bf16_f32 v169, v132, v133
	v_cvt_pk_bf16_f32 v170, v138, v139
	v_cvt_pk_bf16_f32 v171, v140, v141
	v_cvt_pk_bf16_f32 v172, v118, v119
	v_cvt_pk_bf16_f32 v173, v120, v121
	v_cvt_pk_bf16_f32 v174, v126, v127
	v_cvt_pk_bf16_f32 v175, v128, v129
	v_cvt_pk_bf16_f32 v176, v134, v135
	v_cvt_pk_bf16_f32 v177, v136, v137
	v_cvt_pk_bf16_f32 v178, v142, v143
	v_cvt_pk_bf16_f32 v179, v144, v145
	ds_read_b64_tr_b16 v[180:181], v230 offset:0
	ds_read_b64_tr_b16 v[182:183], v230 offset:4096
	ds_read_b64_tr_b16 v[184:185], v230 offset:8192
	ds_read_b64_tr_b16 v[186:187], v230 offset:12288
	ds_read_b64_tr_b16 v[188:189], v231 offset:0
	ds_read_b64_tr_b16 v[190:191], v231 offset:4096
	ds_read_b64_tr_b16 v[192:193], v231 offset:8192
	ds_read_b64_tr_b16 v[194:195], v231 offset:12288
	s_waitcnt lgkmcnt(6)
	v_mfma_f32_16x16x32_bf16 v[2:5], v[180:183], v[164:167], v[2:5]
	v_mfma_f32_16x16x32_bf16 v[6:9], v[180:183], v[172:175], v[6:9]
	ds_read_b64_tr_b16 v[180:181], v230 offset:512
	ds_read_b64_tr_b16 v[182:183], v230 offset:4608
	s_waitcnt lgkmcnt(6)
	v_mfma_f32_16x16x32_bf16 v[2:5], v[184:187], v[168:171], v[2:5]
	v_mfma_f32_16x16x32_bf16 v[6:9], v[184:187], v[176:179], v[6:9]
	ds_read_b64_tr_b16 v[184:185], v230 offset:8704
	ds_read_b64_tr_b16 v[186:187], v230 offset:12800
	s_waitcnt lgkmcnt(6)
	v_mfma_f32_16x16x32_bf16 v[10:13], v[188:191], v[164:167], v[10:13]
	v_mfma_f32_16x16x32_bf16 v[14:17], v[188:191], v[172:175], v[14:17]
	ds_read_b64_tr_b16 v[188:189], v231 offset:512
	ds_read_b64_tr_b16 v[190:191], v231 offset:4608
	s_waitcnt lgkmcnt(6)
	v_mfma_f32_16x16x32_bf16 v[10:13], v[192:195], v[168:171], v[10:13]
	v_mfma_f32_16x16x32_bf16 v[14:17], v[192:195], v[176:179], v[14:17]
	ds_read_b64_tr_b16 v[192:193], v231 offset:8704
	ds_read_b64_tr_b16 v[194:195], v231 offset:12800
	s_waitcnt lgkmcnt(6)
; #define PV_RD(S, d0) do { constexpr int b_ = (d0) * 512; TRRD(S##l0, b_); TRRD(S##h0, b_ + KS_ / 2); TRRD(S##l1, b_ + KS_); TRRD(S##h1, b_ + KS_ + KS_ / 2); TRRD(S##l2, b_ + 2 * KS_); TRRD(S##h2, b_ + 2 * KS_ + KS_ / 2); TRRD(S##l3, b_ + 3 * KS_); TRRD(S##h3, b_ + 3 * KS_ + KS_ / 2); } while (0)
; #define WL(n) do { asm volatile("s_waitcnt lgkmcnt(" #n ")" ::: "memory"); SBAR(); } while (0)
; template <int NCB> __device__ __forceinline__ void pv_tile(f32x16* o, int vb, bf16x8 pa0, bf16x8 pa1, bf16x8 pa2, bf16x8 pa3) {
;     ...
;     constexpr int KS_ = NCB * 1024;
;     ...
;     s16x4 Al0, Al1, Al2, Al3, Ah0, Ah1, Ah2, Ah3, Bl0, Bl1, Bl2, Bl3, Bh0, Bh1, Bh2, Bh3;
;     PV_RD(A, 0); PV_RD(B, 1); WL(8); PV_MM(A, 0);
;     if constexpr (NCB == 4) { PV_RD(A, 2); WL(8); PV_MM(B, 1); PV_RD(B, 3); WL(8); PV_MM(A, 2); WL(0); PV_MM(B, 3); }
;     else { WL(0); PV_MM(B, 1); }
	v_mfma_f32_16x16x32_bf16 v[18:21], v[180:183], v[164:167], v[18:21]
	v_mfma_f32_16x16x32_bf16 v[22:25], v[180:183], v[172:175], v[22:25]
	ds_read_b64_tr_b16 v[180:181], v230 offset:1024
	ds_read_b64_tr_b16 v[182:183], v230 offset:5120
	s_waitcnt lgkmcnt(6)
	v_mfma_f32_16x16x32_bf16 v[18:21], v[184:187], v[168:171], v[18:21]
	v_mfma_f32_16x16x32_bf16 v[22:25], v[184:187], v[176:179], v[22:25]
	ds_read_b64_tr_b16 v[184:185], v230 offset:9216
	ds_read_b64_tr_b16 v[186:187], v230 offset:13312
	s_waitcnt lgkmcnt(6)
	v_mfma_f32_16x16x32_bf16 v[26:29], v[188:191], v[164:167], v[26:29]
	v_mfma_f32_16x16x32_bf16 v[30:33], v[188:191], v[172:175], v[30:33]
	ds_read_b64_tr_b16 v[188:189], v231 offset:1024
	ds_read_b64_tr_b16 v[190:191], v231 offset:5120
	s_waitcnt lgkmcnt(6)
	v_mfma_f32_16x16x32_bf16 v[26:29], v[192:195], v[168:171], v[26:29]
	v_mfma_f32_16x16x32_bf16 v[30:33], v[192:195], v[176:179], v[30:33]
	ds_read_b64_tr_b16 v[192:193], v231 offset:9216
	ds_read_b64_tr_b16 v[194:195], v231 offset:13312
	s_waitcnt lgkmcnt(6)
	v_mfma_f32_16x16x32_bf16 v[34:37], v[180:183], v[164:167], v[34:37]
	v_mfma_f32_16x16x32_bf16 v[38:41], v[180:183], v[172:175], v[38:41]
	ds_read_b64_tr_b16 v[180:181], v230 offset:1536
	ds_read_b64_tr_b16 v[182:183], v230 offset:5632
	s_waitcnt lgkmcnt(6)
	v_mfma_f32_16x16x32_bf16 v[34:37], v[184:187], v[168:171], v[34:37]
	v_mfma_f32_16x16x32_bf16 v[38:41], v[184:187], v[176:179], v[38:41]
	ds_read_b64_tr_b16 v[184:185], v230 offset:9728
	ds_read_b64_tr_b16 v[186:187], v230 offset:13824
	s_waitcnt lgkmcnt(6)
	v_mfma_f32_16x16x32_bf16 v[42:45], v[188:191], v[164:167], v[42:45]
	v_mfma_f32_16x16x32_bf16 v[46:49], v[188:191], v[172:175], v[46:49]
	ds_read_b64_tr_b16 v[188:189], v231 offset:1536
	ds_read_b64_tr_b16 v[190:191], v231 offset:5632
	s_waitcnt lgkmcnt(6)
	v_mfma_f32_16x16x32_bf16 v[42:45], v[192:195], v[168:171], v[42:45]
	v_mfma_f32_16x16x32_bf16 v[46:49], v[192:195], v[176:179], v[46:49]
	ds_read_b64_tr_b16 v[192:193], v231 offset:9728
	ds_read_b64_tr_b16 v[194:195], v231 offset:13824
	s_waitcnt lgkmcnt(6)
	v_mfma_f32_16x16x32_bf16 v[50:53], v[180:183], v[164:167], v[50:53]
	v_mfma_f32_16x16x32_bf16 v[54:57], v[180:183], v[172:175], v[54:57]
	s_waitcnt lgkmcnt(4)
	v_mfma_f32_16x16x32_bf16 v[50:53], v[184:187], v[168:171], v[50:53]
	v_mfma_f32_16x16x32_bf16 v[54:57], v[184:187], v[176:179], v[54:57]
	s_waitcnt lgkmcnt(2)
	v_mfma_f32_16x16x32_bf16 v[58:61], v[188:191], v[164:167], v[58:61]
	v_mfma_f32_16x16x32_bf16 v[62:65], v[188:191], v[172:175], v[62:65]
	s_waitcnt lgkmcnt(0)
	v_mfma_f32_16x16x32_bf16 v[58:61], v[192:195], v[168:171], v[58:61]
	v_mfma_f32_16x16x32_bf16 v[62:65], v[192:195], v[176:179], v[62:65]
; __device__ __forceinline__ int crow(int r, int hi) { return (r & 3) + 8 * (r >> 2) + 4 * hi; }
; __device__ __forceinline__ unsigned cvtpk(float lo, float hi) { f32x2_cv v = {lo, hi}; bf16x2_cv b = __builtin_convertvector(v, bf16x2_cv); return __builtin_bit_cast(unsigned, b); }
; #define WRITET(bf) do { if constexpr (!MLA) { *(LAS bf16x8*)(K_lds + (bf) * KBYTES + kws) = sk0; *(LAS bf16x8*)(V_lds + (bf) * VBYTES + vst0) = sv0; } } while (0)
; __device__ __forceinline__ void finishSM(f32x16& p0, f32x16& p1, float alpha, float& l_reg, bf16x8& pa0, bf16x8& pa1, bf16x8& pa2, bf16x8& pa3) {
;     ...
;     { auto rr = __builtin_amdgcn_permlane32_swap(__float_as_uint(ps), __float_as_uint(ps), false, false);
;       ps = __uint_as_float(rr[0]) + __uint_as_float(rr[1]); }
;     l_reg = l_reg * alpha + ps;
; template <bool MLA> __device__ __forceinline__ void attn_unit(const AttnP& P, int b, int hh, int qb, LAS char* lds) {
;     ...
;         if (t + 1 < NT) { asm volatile("s_waitcnt vmcnt(0)" ::: "memory"); WRITET(buf ^ 1); }
;         __syncthreads();
;     }
;     if (hi == 0) li_l[r32] = l_reg; asm volatile("s_waitcnt lgkmcnt(0)" ::: "memory");
;     bf16_t* Ow = (MLA ? P.QN + (rowbase + qlo) * 2048 + hh * 128 : P.QS + (rowbase + qlo) * 2048 + hh * 64);
; #pragma unroll
;     for (int r = 0; r < 16; ++r) { const int orow = crow(r, hi); const float rl = __builtin_amdgcn_rcpf(li_l[orow]);
; #pragma unroll
;         for (int d0 = 0; d0 < NCB; ++d0) { const float v = o[d0][r] * rl; const float vn = __shfl_xor(v, 1);
;             if ((r32 & 1) == 0) *(unsigned*)(Ow + (size_t)orow * 2048 + d0 * 32 + r32) = cvtpk(v, vn); } }
.Lm16_tile_end:
	s_waitcnt vmcnt(0) lgkmcnt(0)
	s_barrier
	s_add_u32 s41, s41, 1
	s_add_u32 s42, s42, 64
	s_cmp_lt_u32 s41, s40
	s_cbranch_scc1 .Lm16_tile
	s_nop 7
	v_add_f32_e32 v250, v250, v251
	v_add_f32_e32 v216, v216, v217
	v_mov_b32_e32 v217, v250
	s_nop 0
	ds_bpermute_b32 v221, v246, v216
	s_waitcnt lgkmcnt(0)
	v_add_f32_e32 v216, v216, v221
	ds_bpermute_b32 v221, v247, v216
	s_waitcnt lgkmcnt(0)
	v_add_f32_e32 v216, v216, v221
	v_rcp_f32_e32 v216, v216
	ds_bpermute_b32 v221, v246, v217
	s_waitcnt lgkmcnt(0)
	v_add_f32_e32 v217, v217, v221
	ds_bpermute_b32 v221, v247, v217
	s_waitcnt lgkmcnt(0)
	v_add_f32_e32 v217, v217, v221
	v_rcp_f32_e32 v217, v217
	s_nop 0
	v_mul_f32_e32 v2, v2, v216
	v_mul_f32_e32 v3, v3, v216
	v_mul_f32_e32 v4, v4, v216
	v_mul_f32_e32 v5, v5, v216
	v_cvt_pk_bf16_f32 v2, v2, v3
	v_cvt_pk_bf16_f32 v3, v4, v5
	global_store_dwordx2 v241, v[2:3], s[66:67] offset:0
	v_mul_f32_e32 v6, v6, v217
	v_mul_f32_e32 v7, v7, v217
	v_mul_f32_e32 v8, v8, v217
	v_mul_f32_e32 v9, v9, v217
	v_cvt_pk_bf16_f32 v6, v6, v7
	v_cvt_pk_bf16_f32 v7, v8, v9
	global_store_dwordx2 v242, v[6:7], s[66:67] offset:0
	v_mul_f32_e32 v10, v10, v216
	v_mul_f32_e32 v11, v11, v216
	v_mul_f32_e32 v12, v12, v216
	v_mul_f32_e32 v13, v13, v216
	v_cvt_pk_bf16_f32 v10, v10, v11
	v_cvt_pk_bf16_f32 v11, v12, v13
	global_store_dwordx2 v241, v[10:11], s[66:67] offset:32
	v_mul_f32_e32 v14, v14, v217
	v_mul_f32_e32 v15, v15, v217
	v_mul_f32_e32 v16, v16, v217
	v_mul_f32_e32 v17, v17, v217
	v_cvt_pk_bf16_f32 v14, v14, v15
	v_cvt_pk_bf16_f32 v15, v16, v17
	global_store_dwordx2 v242, v[14:15], s[66:67] offset:32
	v_mul_f32_e32 v18, v18, v216
	v_mul_f32_e32 v19, v19, v216
	v_mul_f32_e32 v20, v20, v216
	v_mul_f32_e32 v21, v21, v216
	v_cvt_pk_bf16_f32 v18, v18, v19
	v_cvt_pk_bf16_f32 v19, v20, v21
	global_store_dwordx2 v241, v[18:19], s[66:67] offset:64
	v_mul_f32_e32 v22, v22, v217
	v_mul_f32_e32 v23, v23, v217
	v_mul_f32_e32 v24, v24, v217
	v_mul_f32_e32 v25, v25, v217
	v_cvt_pk_bf16_f32 v22, v22, v23
	v_cvt_pk_bf16_f32 v23, v24, v25
	global_store_dwordx2 v242, v[22:23], s[66:67] offset:64
	v_mul_f32_e32 v26, v26, v216
	v_mul_f32_e32 v27, v27, v216
	v_mul_f32_e32 v28, v28, v216
	v_mul_f32_e32 v29, v29, v216
	v_cvt_pk_bf16_f32 v26, v26, v27
	v_cvt_pk_bf16_f32 v27, v28, v29
	global_store_dwordx2 v241, v[26:27], s[66:67] offset:96
	v_mul_f32_e32 v30, v30, v217
	v_mul_f32_e32 v31, v31, v217
	v_mul_f32_e32 v32, v32, v217
	v_mul_f32_e32 v33, v33, v217
	v_cvt_pk_bf16_f32 v30, v30, v31
	v_cvt_pk_bf16_f32 v31, v32, v33
	global_store_dwordx2 v242, v[30:31], s[66:67] offset:96
	v_mul_f32_e32 v34, v34, v216
	v_mul_f32_e32 v35, v35, v216
	v_mul_f32_e32 v36, v36, v216
	v_mul_f32_e32 v37, v37, v216
	v_cvt_pk_bf16_f32 v34, v34, v35
	v_cvt_pk_bf16_f32 v35, v36, v37
	global_store_dwordx2 v241, v[34:35], s[66:67] offset:128
	v_mul_f32_e32 v38, v38, v217
	v_mul_f32_e32 v39, v39, v217
	v_mul_f32_e32 v40, v40, v217
	v_mul_f32_e32 v41, v41, v217
	v_cvt_pk_bf16_f32 v38, v38, v39
	v_cvt_pk_bf16_f32 v39, v40, v41
	global_store_dwordx2 v242, v[38:39], s[66:67] offset:128
	v_mul_f32_e32 v42, v42, v216
	v_mul_f32_e32 v43, v43, v216
	v_mul_f32_e32 v44, v44, v216
	v_mul_f32_e32 v45, v45, v216
	v_cvt_pk_bf16_f32 v42, v42, v43
	v_cvt_pk_bf16_f32 v43, v44, v45
	global_store_dwordx2 v241, v[42:43], s[66:67] offset:160
	v_mul_f32_e32 v46, v46, v217
	v_mul_f32_e32 v47, v47, v217
	v_mul_f32_e32 v48, v48, v217
	v_mul_f32_e32 v49, v49, v217
	v_cvt_pk_bf16_f32 v46, v46, v47
	v_cvt_pk_bf16_f32 v47, v48, v49
	global_store_dwordx2 v242, v[46:47], s[66:67] offset:160
	v_mul_f32_e32 v50, v50, v216
	v_mul_f32_e32 v51, v51, v216
	v_mul_f32_e32 v52, v52, v216
	v_mul_f32_e32 v53, v53, v216
	v_cvt_pk_bf16_f32 v50, v50, v51
	v_cvt_pk_bf16_f32 v51, v52, v53
	global_store_dwordx2 v241, v[50:51], s[66:67] offset:192
	v_mul_f32_e32 v54, v54, v217
	v_mul_f32_e32 v55, v55, v217
	v_mul_f32_e32 v56, v56, v217
	v_mul_f32_e32 v57, v57, v217
	v_cvt_pk_bf16_f32 v54, v54, v55
	v_cvt_pk_bf16_f32 v55, v56, v57
	global_store_dwordx2 v242, v[54:55], s[66:67] offset:192
	v_mul_f32_e32 v58, v58, v216
	v_mul_f32_e32 v59, v59, v216
	v_mul_f32_e32 v60, v60, v216
	v_mul_f32_e32 v61, v61, v216
	v_cvt_pk_bf16_f32 v58, v58, v59
	v_cvt_pk_bf16_f32 v59, v60, v61
	global_store_dwordx2 v241, v[58:59], s[66:67] offset:224
	v_mul_f32_e32 v62, v62, v217
	v_mul_f32_e32 v63, v63, v217
	v_mul_f32_e32 v64, v64, v217
	v_mul_f32_e32 v65, v65, v217
	v_cvt_pk_bf16_f32 v62, v62, v63
	v_cvt_pk_bf16_f32 v63, v64, v65
	global_store_dwordx2 v242, v[62:63], s[66:67] offset:224
	s_add_u32 s29, s29, 1
	s_cmp_lt_u32 s29, 2
	s_cbranch_scc1 .Lm16_unit
	s_add_u32 s28, s28, s3
	s_cmp_lt_u32 s28, 0x400
	s_cbranch_scc1 .Lm16_item
	s_waitcnt vmcnt(0) lgkmcnt(0)
